# Conv inside the S5 chunk loop: inputs land in LDS by LDS-DMA two chunk iterations ahead (double-buffered per-wave landing zones)
# speedup vs baseline: 1.0601x; 1.0024x over previous
.LBB0_1089:
	s_and_b32 s42, s44, 31
	s_lshl_b32 s42, s42, 5
	s_mov_b32 s43, s3
	v_lshl_add_u64 v[114:115], s[40:41], 0, v[66:67]
	v_mov_b32_e32 v66, v67
	v_lshl_add_u64 v[112:113], v[84:85], 0, s[42:43]
	v_cndmask_b32_e64 v109, v16, v138, s[6:7]
	v_cndmask_b32_e64 v144, v17, v139, s[6:7]
	v_cndmask_b32_e64 v145, v18, v140, s[6:7]
	v_cndmask_b32_e64 v146, v19, v141, s[6:7]
	v_lshl_add_u64 v[116:117], v[82:83], 0, s[36:37]
	v_lshl_add_u64 v[110:111], v[86:87], 0, s[2:3]
	v_lshl_add_u64 v[118:119], v[78:79], 0, s[2:3]
	v_xor_b32_e32 v62, 0x80000000, v63
	v_mov_b32_e32 v61, v60
	v_lshl_add_u64 v[120:121], v[94:95], 0, s[38:39]
	s_mov_b32 s40, 0
	s_movk_i32 s2, 0xffc0
	v_mov_b64_e32 v[122:123], v[66:67]
	s_waitcnt lgkmcnt(0)
	v_lshrrev_b32_e32 v204, 6, v206
	v_and_b32_e32 v205, 63, v206
	v_readfirstlane_b32 s72, v204
	s_load_dwordx2 s[58:59], s[0:1], 0xf0
	s_load_dwordx2 s[70:71], s[0:1], 0xd8
	v_lshlrev_b32_e32 v204, 5, v205
	v_lshlrev_b32_e32 v205, 4, v205
	s_mov_b32 s54, 0
	s_mov_b32 s55, 0
	s_mov_b32 s85, 0
	s_mov_b32 s90, 102400
	s_cmp_eq_u32 s72, 6
	s_cselect_b32 s90, 116736, s90
	s_cmp_eq_u32 s72, 7
	s_cselect_b32 s90, 133120, s90
	s_waitcnt lgkmcnt(0)
	s_add_u32 s60, s58, 0xc000000
	s_addc_u32 s61, s59, 0
	s_add_u32 s58, s58, 0x10000000
	s_addc_u32 s59, s59, 0
	global_load_dwordx4 v[208:211], v204, s[70:71]
	global_load_dwordx4 v[212:215], v204, s[70:71] offset:16
	s_add_u32 s70, s70, 0x800
	s_addc_u32 s71, s71, 0
	global_load_dwordx4 v[216:219], v204, s[70:71]
	global_load_dwordx4 v[220:223], v204, s[70:71] offset:16
	s_add_u32 s70, s70, 0x800
	s_addc_u32 s71, s71, 0
	global_load_dwordx4 v[224:227], v204, s[70:71]
	global_load_dwordx4 v[228:231], v204, s[70:71] offset:16
	s_waitcnt vmcnt(0)
	s_mov_b32 s71, 0
	v_add_u32_e32 v204, 0x400, v205
	v_add_u32_e32 v252, 0x800, v205
	v_add_u32_e32 v253, 0xc00, v205
	s_barrier
	s_branch .LBB0_1092

.Ls5T_noperm_0:
	s_cmp_eq_u32 s71, 0
	s_cbranch_scc1 .Ls5T_w0_0
	s_waitcnt vmcnt(7)
	s_branch .Ls5T_mov_0

.Ls5T_mov_0:
	v_mov_b64_e32 v[54:55], v[6:7]
	v_mov_b64_e32 v[58:59], v[2:3]
	v_mov_b64_e32 v[52:53], v[4:5]
	v_mov_b64_e32 v[56:57], v[0:1]

.LBB0_1092:
	s_and_b64 vcc, exec, s[28:29]
	s_cbranch_vccz .LBB0_1107
	s_mov_b32 s100, 0
	s_mov_b32 s71, 0
	s_cmp_lt_u32 s72, 5
	s_cbranch_scc1 .Lcv_topdone_0
	s_cmp_eq_u32 s54, 0
	s_cbranch_scc1 .Lcv_noprev_0
	v_add_u32_e32 v200, s84, v205
	ds_read_b128 v[232:235], v200 offset:0
	ds_read_b128 v[236:239], v200 offset:1024
	ds_read_b128 v[240:243], v200 offset:2048
	ds_read_b128 v[244:247], v200 offset:3072
	ds_read_b128 v[248:251], v200 offset:4096
	ds_read_b128 v[184:187], v200 offset:5120
	ds_read_b128 v[188:191], v200 offset:6144
	s_and_b32 s70, s56, 0xfff
	s_waitcnt lgkmcnt(0)
	v_lshlrev_b32_e32 v200, 16, v232
	v_and_b32_e32 v201, 0xffff0000, v232
	v_lshlrev_b32_e32 v202, 16, v236
	v_and_b32_e32 v203, 0xffff0000, v236
	v_pk_mul_f32 v[200:201], v[208:209], v[200:201]
	v_pk_mul_f32 v[192:193], v[200:201], v[202:203]
	v_lshlrev_b32_e32 v200, 16, v233
	v_and_b32_e32 v201, 0xffff0000, v233
	v_lshlrev_b32_e32 v202, 16, v237
	v_and_b32_e32 v203, 0xffff0000, v237
	v_pk_mul_f32 v[200:201], v[210:211], v[200:201]
	v_pk_mul_f32 v[194:195], v[200:201], v[202:203]
	v_lshlrev_b32_e32 v200, 16, v234
	v_and_b32_e32 v201, 0xffff0000, v234
	v_lshlrev_b32_e32 v202, 16, v238
	v_and_b32_e32 v203, 0xffff0000, v238
	v_pk_mul_f32 v[200:201], v[212:213], v[200:201]
	v_pk_mul_f32 v[196:197], v[200:201], v[202:203]
	v_lshlrev_b32_e32 v200, 16, v235
	v_and_b32_e32 v201, 0xffff0000, v235
	v_lshlrev_b32_e32 v202, 16, v239
	v_and_b32_e32 v203, 0xffff0000, v239
	v_pk_mul_f32 v[200:201], v[214:215], v[200:201]
	v_pk_mul_f32 v[198:199], v[200:201], v[202:203]
	s_cmp_lt_u32 s70, 1
	s_cbranch_scc1 .Lcv_taps_done_0
	v_lshlrev_b32_e32 v200, 16, v240
	v_and_b32_e32 v201, 0xffff0000, v240
	v_lshlrev_b32_e32 v202, 16, v244
	v_and_b32_e32 v203, 0xffff0000, v244
	v_pk_mul_f32 v[200:201], v[216:217], v[200:201]
	v_pk_fma_f32 v[192:193], v[200:201], v[202:203], v[192:193]
	v_lshlrev_b32_e32 v200, 16, v241
	v_and_b32_e32 v201, 0xffff0000, v241
	v_lshlrev_b32_e32 v202, 16, v245
	v_and_b32_e32 v203, 0xffff0000, v245
	v_pk_mul_f32 v[200:201], v[218:219], v[200:201]
	v_pk_fma_f32 v[194:195], v[200:201], v[202:203], v[194:195]
	v_lshlrev_b32_e32 v200, 16, v242
	v_and_b32_e32 v201, 0xffff0000, v242
	v_lshlrev_b32_e32 v202, 16, v246
	v_and_b32_e32 v203, 0xffff0000, v246
	v_pk_mul_f32 v[200:201], v[220:221], v[200:201]
	v_pk_fma_f32 v[196:197], v[200:201], v[202:203], v[196:197]
	v_lshlrev_b32_e32 v200, 16, v243
	v_and_b32_e32 v201, 0xffff0000, v243
	v_lshlrev_b32_e32 v202, 16, v247
	v_and_b32_e32 v203, 0xffff0000, v247
	v_pk_mul_f32 v[200:201], v[222:223], v[200:201]
	v_pk_fma_f32 v[198:199], v[200:201], v[202:203], v[198:199]
	s_cmp_lt_u32 s70, 2
	s_cbranch_scc1 .Lcv_taps_done_0
	v_lshlrev_b32_e32 v200, 16, v248
	v_and_b32_e32 v201, 0xffff0000, v248
	v_lshlrev_b32_e32 v202, 16, v184
	v_and_b32_e32 v203, 0xffff0000, v184
	v_pk_mul_f32 v[200:201], v[224:225], v[200:201]
	v_pk_fma_f32 v[192:193], v[200:201], v[202:203], v[192:193]
	v_lshlrev_b32_e32 v200, 16, v249
	v_and_b32_e32 v201, 0xffff0000, v249
	v_lshlrev_b32_e32 v202, 16, v185
	v_and_b32_e32 v203, 0xffff0000, v185
	v_pk_mul_f32 v[200:201], v[226:227], v[200:201]
	v_pk_fma_f32 v[194:195], v[200:201], v[202:203], v[194:195]
	v_lshlrev_b32_e32 v200, 16, v250
	v_and_b32_e32 v201, 0xffff0000, v250
	v_lshlrev_b32_e32 v202, 16, v186
	v_and_b32_e32 v203, 0xffff0000, v186
	v_pk_mul_f32 v[200:201], v[228:229], v[200:201]
	v_pk_fma_f32 v[196:197], v[200:201], v[202:203], v[196:197]
	v_lshlrev_b32_e32 v200, 16, v251
	v_and_b32_e32 v201, 0xffff0000, v251
	v_lshlrev_b32_e32 v202, 16, v187
	v_and_b32_e32 v203, 0xffff0000, v187
	v_pk_mul_f32 v[200:201], v[230:231], v[200:201]
	v_pk_fma_f32 v[198:199], v[200:201], v[202:203], v[198:199]

.Lcv_noprev_0:
	s_mov_b32 s54, s85
	s_mov_b32 s56, s86
	s_mov_b64 s[68:69], s[88:89]
	s_mov_b32 s84, s87
	s_mov_b32 s85, 0

.LBB0_1106:
	s_cmp_lt_u32 s72, 5
	s_cbranch_scc1 .Lcv_done_0
	s_cmp_ge_u32 s55, 43
	s_cbranch_scc1 .Lcv_done_0
	s_mul_i32 s57, s55, 0x300
	s_mul_i32 s70, s96, 3
	s_add_u32 s57, s57, s70
	s_add_u32 s57, s57, s72
	s_sub_u32 s57, s57, 5
	s_cmp_ge_u32 s57, 0x8000
	s_cbranch_scc1 .Lcv_noissue_0
	s_lshl_b32 s70, s57, 12
	s_add_u32 s62, s58, s70
	s_addc_u32 s63, s59, 0
	s_sub_u32 s64, s62, 0x1000
	s_subb_u32 s65, s63, 0
	s_sub_u32 s66, s62, 0x2000
	s_subb_u32 s67, s63, 0
	s_lshl_b32 s70, s57, 11
	s_add_u32 s88, s60, s70
	s_addc_u32 s89, s61, 0
	s_and_b32 s70, s55, 1
	s_mul_i32 s70, s70, 0x1c00
	s_add_u32 s87, s90, s70
	s_mov_b32 s70, m0
	s_add_u32 m0, s87, 0
	s_nop 0
	global_load_lds_dwordx4 v252, s[62:63]
	s_add_u32 m0, s87, 1024
	s_nop 0
	global_load_lds_dwordx4 v253, s[62:63]
	s_add_u32 m0, s87, 2048
	s_nop 0
	global_load_lds_dwordx4 v252, s[64:65]
	s_add_u32 m0, s87, 3072
	s_nop 0
	global_load_lds_dwordx4 v253, s[64:65]
	s_add_u32 m0, s87, 4096
	s_nop 0
	global_load_lds_dwordx4 v252, s[66:67]
	s_add_u32 m0, s87, 5120
	s_nop 0
	global_load_lds_dwordx4 v253, s[66:67]
	s_add_u32 m0, s87, 6144
	s_nop 0
	global_load_lds_dwordx4 v204, s[62:63]
	s_mov_b32 m0, s70
	s_mov_b32 s86, s57
	s_mov_b32 s85, 1
	s_mov_b32 s71, 1
	s_add_u32 s55, s55, 1
	s_branch .Lcv_done_0
.Lcv_noissue_0:
	s_mov_b32 s55, 43

.LBB0_2569:
	s_and_b32 s2, s44, 31
	s_lshl_b32 s2, s2, 5
	v_lshl_add_u64 v[112:113], v[84:85], 0, s[2:3]
	v_lshl_add_u64 v[114:115], s[40:41], 0, v[66:67]
	s_lshl_b32 s2, s53, 1
	v_mov_b32_e32 v66, v67
	v_cndmask_b32_e64 v109, v16, v138, s[6:7]
	v_cndmask_b32_e64 v144, v17, v139, s[6:7]
	v_cndmask_b32_e64 v145, v18, v140, s[6:7]
	v_cndmask_b32_e64 v146, v19, v141, s[6:7]
	v_lshl_add_u64 v[116:117], v[82:83], 0, s[36:37]
	v_lshl_add_u64 v[110:111], v[86:87], 0, s[2:3]
	v_lshl_add_u64 v[118:119], v[78:79], 0, s[2:3]
	v_xor_b32_e32 v62, 0x80000000, v63
	v_mov_b32_e32 v61, v60
	v_lshl_add_u64 v[120:121], v[94:95], 0, s[38:39]
	s_mov_b32 s40, 0
	s_movk_i32 s2, 0xffc0
	v_mov_b64_e32 v[122:123], v[66:67]
	s_waitcnt lgkmcnt(0)
	v_lshrrev_b32_e32 v204, 6, v206
	v_and_b32_e32 v205, 63, v206
	v_readfirstlane_b32 s72, v204
	s_load_dwordx2 s[58:59], s[0:1], 0xf0
	s_load_dwordx2 s[70:71], s[0:1], 0xd8
	v_lshlrev_b32_e32 v204, 5, v205
	v_lshlrev_b32_e32 v205, 4, v205
	s_mov_b32 s54, 0
	s_mov_b32 s55, 0
	s_mov_b32 s85, 0
	s_mov_b32 s90, 102400
	s_cmp_eq_u32 s72, 6
	s_cselect_b32 s90, 116736, s90
	s_cmp_eq_u32 s72, 7
	s_cselect_b32 s90, 133120, s90
	s_waitcnt lgkmcnt(0)
	s_add_u32 s60, s58, 0xc000000
	s_addc_u32 s61, s59, 0
	s_add_u32 s58, s58, 0x10000000
	s_addc_u32 s59, s59, 0
	s_add_u32 s70, s70, 0x1800
	s_addc_u32 s71, s71, 0
	global_load_dwordx4 v[208:211], v204, s[70:71]
	global_load_dwordx4 v[212:215], v204, s[70:71] offset:16
	s_add_u32 s70, s70, 0x800
	s_addc_u32 s71, s71, 0
	global_load_dwordx4 v[216:219], v204, s[70:71]
	global_load_dwordx4 v[220:223], v204, s[70:71] offset:16
	s_add_u32 s70, s70, 0x800
	s_addc_u32 s71, s71, 0
	global_load_dwordx4 v[224:227], v204, s[70:71]
	global_load_dwordx4 v[228:231], v204, s[70:71] offset:16
	s_waitcnt vmcnt(0)
	s_mov_b32 s71, 0
	v_add_u32_e32 v204, 0x400, v205
	v_add_u32_e32 v252, 0x800, v205
	v_add_u32_e32 v253, 0xc00, v205
	s_barrier
	s_branch .LBB0_2572

.LBB0_2586:
	s_cmp_lt_u32 s72, 5
	s_cbranch_scc1 .Lcv_done_1
	s_cmp_ge_u32 s55, 43
	s_cbranch_scc1 .Lcv_done_1
	s_mul_i32 s57, s55, 0x300
	s_mul_i32 s70, s95, 3
	s_add_u32 s57, s57, s70
	s_add_u32 s57, s57, s72
	s_sub_u32 s57, s57, 5
	s_cmp_ge_u32 s57, 0x8000
	s_cbranch_scc1 .Lcv_noissue_1
	s_lshl_b32 s70, s57, 12
	s_add_u32 s62, s58, s70
	s_addc_u32 s63, s59, 0
	s_sub_u32 s64, s62, 0x1000
	s_subb_u32 s65, s63, 0
	s_sub_u32 s66, s62, 0x2000
	s_subb_u32 s67, s63, 0
	s_lshl_b32 s70, s57, 11
	s_add_u32 s88, s60, s70
	s_addc_u32 s89, s61, 0
	s_and_b32 s70, s55, 1
	s_mul_i32 s70, s70, 0x1c00
	s_add_u32 s87, s90, s70
	s_mov_b32 s70, m0
	s_add_u32 m0, s87, 0
	s_nop 0
	global_load_lds_dwordx4 v252, s[62:63]
	s_add_u32 m0, s87, 1024
	s_nop 0
	global_load_lds_dwordx4 v253, s[62:63]
	s_add_u32 m0, s87, 2048
	s_nop 0
	global_load_lds_dwordx4 v252, s[64:65]
	s_add_u32 m0, s87, 3072
	s_nop 0
	global_load_lds_dwordx4 v253, s[64:65]
	s_add_u32 m0, s87, 4096
	s_nop 0
	global_load_lds_dwordx4 v252, s[66:67]
	s_add_u32 m0, s87, 5120
	s_nop 0
	global_load_lds_dwordx4 v253, s[66:67]
	s_add_u32 m0, s87, 6144
	s_nop 0
	global_load_lds_dwordx4 v204, s[62:63]
	s_mov_b32 m0, s70
	s_mov_b32 s86, s57
	s_mov_b32 s85, 1
	s_mov_b32 s71, 1
	s_add_u32 s55, s55, 1
	s_branch .Lcv_done_1
